# same as previous best plus a much larger safety cap on the grid-barrier spin (no timing effect intended)
# speedup vs baseline: 1.0068x; 1.0017x over previous
; __device__ __forceinline__ unsigned xb_ld(unsigned* p) { return __hip_atomic_load(p, __ATOMIC_RELAXED, __HIP_MEMORY_SCOPE_AGENT); }
; #define XB_SPIN(cond, bar) do { unsigned _sp = 0; while (cond) { __builtin_amdgcn_s_sleep(1); \
;     if ((++_sp & 255u) == 0u) { if (xb_ld(&(bar)[XB_TMO])) break; if (_sp > XB_SPIN_CAP) { atomicAdd(&(bar)[XB_TMO], 1u); break; } } } } while (0)
; __device__ __forceinline__ void xcd_barrier(const XcdBarrier& b) {
;     ...
;       else XB_SPIN(xb_ld(&bar[XB_TOPGEN]) == tg, bar);
.Lgb0_poll:
	s_mov_b32 s44, 0x100000

; __device__ __forceinline__ unsigned xb_ld(unsigned* p) { return __hip_atomic_load(p, __ATOMIC_RELAXED, __HIP_MEMORY_SCOPE_AGENT); }
; #define XB_SPIN(cond, bar) do { unsigned _sp = 0; while (cond) { __builtin_amdgcn_s_sleep(1); \
;     if ((++_sp & 255u) == 0u) { if (xb_ld(&(bar)[XB_TMO])) break; if (_sp > XB_SPIN_CAP) { atomicAdd(&(bar)[XB_TMO], 1u); break; } } } } while (0)
; __device__ __forceinline__ void xcd_barrier(const XcdBarrier& b) {
;     ...
;       else XB_SPIN(xb_ld(&bar[XB_TOPGEN]) == tg, bar);
.Lgb6_poll:
	s_mov_b32 s46, 0x100000
